# nt hint on the bf16 weight-copy stores in the attention-phase slot (less L2 pollution), on top of v21
# speedup vs baseline: 1.0069x; 1.0005x over previous
.LBB0_427:
	s_ashr_i32 s3, s2, 31
	s_mul_hi_u32 s31, s2, s12
	s_mul_i32 s3, s3, s12
	s_add_i32 s3, s31, s3
	s_mul_i32 s2, s2, s12
	s_lshl_b64 s[2:3], s[2:3], 1
	s_add_u32 s2, s26, s2
	s_addc_u32 s3, s27, s3
	global_store_dword v68, v71, s[2:3] nt
	global_store_dword v68, v73, s[2:3] offset:256 nt
	s_waitcnt lgkmcnt(0)
	s_barrier
	s_andn2_b64 vcc, exec, s[24:25]
	s_mov_b64 s[26:27], s[22:23]
	s_mov_b32 s12, s30
	s_mov_b32 s31, s15
	s_mov_b32 s42, s38
	s_mov_b32 s40, s34
	s_cbranch_vccz .LBB0_492

.LBB0_459:
	s_ashr_i32 s41, s40, 31
	s_xor_b64 s[48:49], s[2:3], -1
	s_lshl_b64 s[2:3], s[40:41], 1
	s_add_u32 s26, s26, s2
	s_addc_u32 s27, s27, s3
	s_ashr_i32 s2, s42, 31
	s_mul_hi_u32 s3, s42, s12
	s_mul_i32 s2, s2, s12
	s_add_i32 s3, s3, s2
	s_mul_i32 s2, s42, s12
	s_lshl_b64 s[2:3], s[2:3], 1
	s_add_u32 s2, s26, s2
	s_addc_u32 s3, s27, s3
	v_lshlrev_b32_e32 v68, 2, v222
	s_waitcnt lgkmcnt(14)
	global_store_dword v68, v98, s[2:3] nt
	global_store_dword v68, v100, s[2:3] offset:256 nt
	v_cndmask_b32_e64 v98, 0, 1, s[48:49]
	v_cmp_ne_u32_e64 s[2:3], 1, v98
	s_andn2_b64 vcc, exec, s[48:49]
	s_add_i32 s40, s39, 8
	s_cbranch_vccnz .LBB0_461
	s_add_i32 s41, s35, s40
	s_lshl_b32 s41, s41, 1
	s_and_b32 s41, s41, -8
	s_lshl_b32 s43, s40, 1
	s_add_i32 s42, s41, s31
	s_and_b32 s41, s40, 0xffffffc0
	s_and_b32 s43, s43, 62
	s_or_b32 s41, s43, s41
	s_bfe_u32 s40, s40, 0x10005
	s_or_b32 s43, s41, s40
	s_and_b64 s[40:41], s[44:45], exec
	s_cselect_b32 s40, s43, s42
.LBB0_461:
	s_ashr_i32 s41, s40, 31
	s_mul_hi_u32 s42, s40, s12
	s_mul_i32 s41, s41, s12
	s_add_i32 s41, s42, s41
	s_mul_i32 s40, s40, s12
	s_lshl_b64 s[40:41], s[40:41], 1
	s_add_u32 s40, s26, s40
	s_addc_u32 s41, s27, s41
	global_store_dword v68, v99, s[40:41] nt
	global_store_dword v68, v101, s[40:41] offset:256 nt
	s_and_b64 vcc, exec, s[2:3]
	s_add_i32 s40, s39, 16
	s_cbranch_vccnz .LBB0_463
	s_add_i32 s41, s35, s40
	s_lshl_b32 s41, s41, 1
	s_and_b32 s41, s41, -8
	s_lshl_b32 s43, s40, 1
	s_add_i32 s42, s41, s31
	s_and_b32 s41, s40, 0xffffffc0
	s_and_b32 s43, s43, 62
	s_or_b32 s41, s43, s41
	s_bfe_u32 s40, s40, 0x10005
	s_or_b32 s43, s41, s40
	s_and_b64 s[40:41], s[44:45], exec
	s_cselect_b32 s40, s43, s42
.LBB0_463:
	s_ashr_i32 s41, s40, 31
	s_mul_hi_u32 s42, s40, s12
	s_mul_i32 s41, s41, s12
	s_add_i32 s41, s42, s41
	s_mul_i32 s40, s40, s12
	s_lshl_b64 s[40:41], s[40:41], 1
	s_add_u32 s40, s26, s40
	s_addc_u32 s41, s27, s41
	s_waitcnt lgkmcnt(13)
	global_store_dword v68, v94, s[40:41] nt
	s_waitcnt lgkmcnt(12)
	global_store_dword v68, v96, s[40:41] offset:256 nt
	s_and_b64 vcc, exec, s[2:3]
	s_add_i32 s40, s39, 24
	s_cbranch_vccnz .LBB0_465
	s_add_i32 s41, s35, s40
	s_lshl_b32 s41, s41, 1
	s_and_b32 s41, s41, -8
	s_lshl_b32 s43, s40, 1
	s_add_i32 s42, s41, s31
	s_and_b32 s41, s40, 0xffffffc0
	s_and_b32 s43, s43, 62
	s_or_b32 s41, s43, s41
	s_bfe_u32 s40, s40, 0x10005
	s_or_b32 s43, s41, s40
	s_and_b64 s[40:41], s[44:45], exec
	s_cselect_b32 s40, s43, s42
.LBB0_465:
	s_ashr_i32 s41, s40, 31
	s_mul_hi_u32 s42, s40, s12
	s_mul_i32 s41, s41, s12
	s_add_i32 s41, s42, s41
	s_mul_i32 s40, s40, s12
	s_lshl_b64 s[40:41], s[40:41], 1
	s_add_u32 s40, s26, s40
	s_addc_u32 s41, s27, s41
	global_store_dword v68, v95, s[40:41] nt
	global_store_dword v68, v97, s[40:41] offset:256 nt
	s_and_b64 vcc, exec, s[2:3]
	s_add_i32 s40, s39, 32
	s_cbranch_vccnz .LBB0_467
	s_add_i32 s41, s35, s40
	s_lshl_b32 s41, s41, 1
	s_and_b32 s41, s41, -8
	s_lshl_b32 s43, s39, 1
	s_add_i32 s42, s41, s31
	s_and_b32 s41, s40, 0xffffffc0
	s_and_b32 s43, s43, 62
	s_or_b32 s41, s43, s41
	s_bfe_u32 s40, s40, 0x10005
	s_or_b32 s43, s41, s40
	s_and_b64 s[40:41], s[44:45], exec
	s_cselect_b32 s40, s43, s42
.LBB0_467:
	s_ashr_i32 s41, s40, 31
	s_mul_hi_u32 s42, s40, s12
	s_mul_i32 s41, s41, s12
	s_add_i32 s41, s42, s41
	s_mul_i32 s40, s40, s12
	s_lshl_b64 s[40:41], s[40:41], 1
	s_add_u32 s40, s26, s40
	s_addc_u32 s41, s27, s41
	s_waitcnt lgkmcnt(11)
	global_store_dword v68, v90, s[40:41] nt
	s_waitcnt lgkmcnt(10)
	global_store_dword v68, v92, s[40:41] offset:256 nt
	s_and_b64 vcc, exec, s[2:3]
	s_add_i32 s40, s39, 40
	s_cbranch_vccnz .LBB0_469
	s_add_i32 s41, s35, s40
	s_lshl_b32 s41, s41, 1
	s_and_b32 s41, s41, -8
	s_lshl_b32 s43, s40, 1
	s_add_i32 s42, s41, s31
	s_and_b32 s41, s40, 0xffffffc0
	s_and_b32 s43, s43, 62
	s_or_b32 s41, s43, s41
	s_bfe_u32 s40, s40, 0x10005
	s_or_b32 s43, s41, s40
	s_and_b64 s[40:41], s[44:45], exec
	s_cselect_b32 s40, s43, s42
.LBB0_469:
	s_ashr_i32 s41, s40, 31
	s_mul_hi_u32 s42, s40, s12
	s_mul_i32 s41, s41, s12
	s_add_i32 s41, s42, s41
	s_mul_i32 s40, s40, s12
	s_lshl_b64 s[40:41], s[40:41], 1
	s_add_u32 s40, s26, s40
	s_addc_u32 s41, s27, s41
	global_store_dword v68, v91, s[40:41] nt
	global_store_dword v68, v93, s[40:41] offset:256 nt
	s_and_b64 vcc, exec, s[2:3]
	s_add_i32 s40, s39, 48
	s_cbranch_vccnz .LBB0_471
	s_add_i32 s41, s35, s40
	s_lshl_b32 s41, s41, 1
	s_and_b32 s41, s41, -8
	s_lshl_b32 s43, s40, 1
	s_add_i32 s42, s41, s31
	s_and_b32 s41, s40, 0xffffffc0
	s_and_b32 s43, s43, 62
	s_or_b32 s41, s43, s41
	s_bfe_u32 s40, s40, 0x10005
	s_or_b32 s43, s41, s40
	s_and_b64 s[40:41], s[44:45], exec
	s_cselect_b32 s40, s43, s42
.LBB0_471:
	s_ashr_i32 s41, s40, 31
	s_mul_hi_u32 s42, s40, s12
	s_mul_i32 s41, s41, s12
	s_add_i32 s41, s42, s41
	s_mul_i32 s40, s40, s12
	s_lshl_b64 s[40:41], s[40:41], 1
	s_add_u32 s40, s26, s40
	s_addc_u32 s41, s27, s41
	s_waitcnt lgkmcnt(9)
	global_store_dword v68, v86, s[40:41] nt
	s_waitcnt lgkmcnt(8)
	global_store_dword v68, v88, s[40:41] offset:256 nt
	s_and_b64 vcc, exec, s[2:3]
	s_add_i32 s40, s39, 56
	s_cbranch_vccnz .LBB0_473
	s_add_i32 s41, s35, s40
	s_lshl_b32 s41, s41, 1
	s_and_b32 s41, s41, -8
	s_lshl_b32 s43, s40, 1
	s_add_i32 s42, s41, s31
	s_and_b32 s41, s40, 0xffffffc0
	s_and_b32 s43, s43, 62
	s_or_b32 s41, s43, s41
	s_bfe_u32 s40, s40, 0x10005
	s_or_b32 s43, s41, s40
	s_and_b64 s[40:41], s[44:45], exec
	s_cselect_b32 s40, s43, s42
.LBB0_473:
	s_ashr_i32 s41, s40, 31
	s_mul_hi_u32 s42, s40, s12
	s_mul_i32 s41, s41, s12
	s_add_i32 s41, s42, s41
	s_mul_i32 s40, s40, s12
	s_lshl_b64 s[40:41], s[40:41], 1
	s_add_u32 s40, s26, s40
	s_addc_u32 s41, s27, s41
	global_store_dword v68, v87, s[40:41] nt
	global_store_dword v68, v89, s[40:41] offset:256 nt
	s_and_b64 vcc, exec, s[2:3]
	s_add_i32 s40, s39, 64
	s_cbranch_vccnz .LBB0_475
	s_add_i32 s41, s35, s40
	s_lshl_b32 s41, s41, 1
	s_and_b32 s41, s41, -8
	s_add_i32 s42, s41, s31
	s_lshl_b32 s41, s39, 1
	s_andn2_b32 s40, s40, 63
	s_and_b32 s41, s41, 62
	s_or_b32 s40, s41, s40
	s_bfe_u32 s41, s39, 0x10005
	s_or_b32 s43, s40, s41
	s_and_b64 s[40:41], s[44:45], exec
	s_cselect_b32 s40, s43, s42
.LBB0_475:
	s_ashr_i32 s41, s40, 31
	s_mul_hi_u32 s42, s40, s12
	s_mul_i32 s41, s41, s12
	s_add_i32 s41, s42, s41
	s_mul_i32 s40, s40, s12
	s_lshl_b64 s[40:41], s[40:41], 1
	s_add_u32 s40, s26, s40
	s_addc_u32 s41, s27, s41
	s_waitcnt lgkmcnt(7)
	global_store_dword v68, v82, s[40:41] nt
	s_waitcnt lgkmcnt(6)
	global_store_dword v68, v84, s[40:41] offset:256 nt
	s_and_b64 vcc, exec, s[2:3]
	s_add_i32 s40, s39, 0x48
	s_cbranch_vccnz .LBB0_477
	s_add_i32 s41, s35, s40
	s_lshl_b32 s41, s41, 1
	s_and_b32 s41, s41, -8
	s_lshl_b32 s43, s40, 1
	s_add_i32 s42, s41, s31
	s_and_b32 s41, s40, 0xffffffc0
	s_and_b32 s43, s43, 62
	s_or_b32 s41, s43, s41
	s_bfe_u32 s40, s40, 0x10005
	s_or_b32 s43, s41, s40
	s_and_b64 s[40:41], s[44:45], exec
	s_cselect_b32 s40, s43, s42
.LBB0_477:
	s_ashr_i32 s41, s40, 31
	s_mul_hi_u32 s42, s40, s12
	s_mul_i32 s41, s41, s12
	s_add_i32 s41, s42, s41
	s_mul_i32 s40, s40, s12
	s_lshl_b64 s[40:41], s[40:41], 1
	s_add_u32 s40, s26, s40
	s_addc_u32 s41, s27, s41
	global_store_dword v68, v83, s[40:41] nt
	global_store_dword v68, v85, s[40:41] offset:256 nt
	s_and_b64 vcc, exec, s[2:3]
	s_add_i32 s40, s39, 0x50
	s_cbranch_vccnz .LBB0_479
	s_add_i32 s41, s35, s40
	s_lshl_b32 s41, s41, 1
	s_and_b32 s41, s41, -8
	s_lshl_b32 s43, s40, 1
	s_add_i32 s42, s41, s31
	s_and_b32 s41, s40, 0xffffffc0
	s_and_b32 s43, s43, 62
	s_or_b32 s41, s43, s41
	s_bfe_u32 s40, s40, 0x10005
	s_or_b32 s43, s41, s40
	s_and_b64 s[40:41], s[44:45], exec
	s_cselect_b32 s40, s43, s42
.LBB0_479:
	s_ashr_i32 s41, s40, 31
	s_mul_hi_u32 s42, s40, s12
	s_mul_i32 s41, s41, s12
	s_add_i32 s41, s42, s41
	s_mul_i32 s40, s40, s12
	s_lshl_b64 s[40:41], s[40:41], 1
	s_add_u32 s40, s26, s40
	s_addc_u32 s41, s27, s41
	s_waitcnt lgkmcnt(5)
	global_store_dword v68, v78, s[40:41] nt
	s_waitcnt lgkmcnt(4)
	global_store_dword v68, v80, s[40:41] offset:256 nt
	s_and_b64 vcc, exec, s[2:3]
	s_add_i32 s40, s39, 0x58
	s_cbranch_vccnz .LBB0_481
	s_add_i32 s41, s35, s40
	s_lshl_b32 s41, s41, 1
	s_and_b32 s41, s41, -8
	s_lshl_b32 s43, s40, 1
	s_add_i32 s42, s41, s31
	s_and_b32 s41, s40, 0xffffffc0
	s_and_b32 s43, s43, 62
	s_or_b32 s41, s43, s41
	s_bfe_u32 s40, s40, 0x10005
	s_or_b32 s43, s41, s40
	s_and_b64 s[40:41], s[44:45], exec
	s_cselect_b32 s40, s43, s42
.LBB0_481:
	s_ashr_i32 s41, s40, 31
	s_mul_hi_u32 s42, s40, s12
	s_mul_i32 s41, s41, s12
	s_add_i32 s41, s42, s41
	s_mul_i32 s40, s40, s12
	s_lshl_b64 s[40:41], s[40:41], 1
	s_add_u32 s40, s26, s40
	s_addc_u32 s41, s27, s41
	global_store_dword v68, v79, s[40:41] nt
	global_store_dword v68, v81, s[40:41] offset:256 nt
	s_and_b64 vcc, exec, s[2:3]
	s_add_i32 s40, s39, 0x60
	s_cbranch_vccnz .LBB0_483
	s_add_i32 s41, s35, s40
	s_lshl_b32 s41, s41, 1
	s_and_b32 s41, s41, -8
	s_lshl_b32 s43, s39, 1
	s_add_i32 s42, s41, s31
	s_and_b32 s41, s40, 0xffffffc0
	s_and_b32 s43, s43, 62
	s_or_b32 s41, s43, s41
	s_bfe_u32 s40, s40, 0x10005
	s_or_b32 s43, s41, s40
	s_and_b64 s[40:41], s[44:45], exec
	s_cselect_b32 s40, s43, s42
.LBB0_483:
	s_ashr_i32 s41, s40, 31
	s_mul_hi_u32 s42, s40, s12
	s_mul_i32 s41, s41, s12
	s_add_i32 s41, s42, s41
	s_mul_i32 s40, s40, s12
	s_lshl_b64 s[40:41], s[40:41], 1
	s_add_u32 s40, s26, s40
	s_addc_u32 s41, s27, s41
	s_waitcnt lgkmcnt(3)
	global_store_dword v68, v74, s[40:41] nt
	s_waitcnt lgkmcnt(2)
	global_store_dword v68, v76, s[40:41] offset:256 nt
	s_and_b64 vcc, exec, s[2:3]
	s_add_i32 s40, s39, 0x68
	s_cbranch_vccnz .LBB0_485
	s_add_i32 s41, s35, s40
	s_lshl_b32 s41, s41, 1
	s_and_b32 s41, s41, -8
	s_lshl_b32 s43, s40, 1
	s_add_i32 s42, s41, s31
	s_and_b32 s41, s40, 0xffffffc0
	s_and_b32 s43, s43, 62
	s_or_b32 s41, s43, s41
	s_bfe_u32 s40, s40, 0x10005
	s_or_b32 s43, s41, s40
	s_and_b64 s[40:41], s[44:45], exec
	s_cselect_b32 s40, s43, s42
.LBB0_485:
	s_ashr_i32 s41, s40, 31
	s_mul_hi_u32 s42, s40, s12
	s_mul_i32 s41, s41, s12
	s_add_i32 s41, s42, s41
	s_mul_i32 s40, s40, s12
	s_lshl_b64 s[40:41], s[40:41], 1
	s_add_u32 s40, s26, s40
	s_addc_u32 s41, s27, s41
	global_store_dword v68, v75, s[40:41] nt
	global_store_dword v68, v77, s[40:41] offset:256 nt
	s_and_b64 vcc, exec, s[2:3]
	s_add_i32 s40, s39, 0x70
	s_cbranch_vccnz .LBB0_487
	s_add_i32 s41, s35, s40
	s_lshl_b32 s41, s41, 1
	s_and_b32 s41, s41, -8
	s_lshl_b32 s43, s40, 1
	s_add_i32 s42, s41, s31
	s_and_b32 s41, s40, 0xffffffc0
	s_and_b32 s43, s43, 62
	s_or_b32 s41, s43, s41
	s_bfe_u32 s40, s40, 0x10005
	s_or_b32 s43, s41, s40
	s_and_b64 s[40:41], s[44:45], exec
	s_cselect_b32 s40, s43, s42
.LBB0_487:
	s_ashr_i32 s41, s40, 31
	s_mul_hi_u32 s42, s40, s12
	s_mul_i32 s41, s41, s12
	s_add_i32 s41, s42, s41
	s_mul_i32 s40, s40, s12
	s_lshl_b64 s[40:41], s[40:41], 1
	s_add_u32 s40, s26, s40
	s_addc_u32 s41, s27, s41
	s_and_b64 vcc, exec, s[2:3]
	s_add_i32 s2, s39, 0x78
	s_waitcnt lgkmcnt(1)
	global_store_dword v68, v70, s[40:41] nt
	s_waitcnt lgkmcnt(0)
	global_store_dword v68, v72, s[40:41] offset:256 nt
	s_cbranch_vccnz .LBB0_427
	s_add_i32 s3, s35, s2
	s_lshl_b32 s3, s3, 1
	s_and_b32 s3, s3, -8
	s_lshl_b32 s35, s2, 1
	s_add_i32 s31, s3, s31
	s_and_b32 s3, s2, 0xffffffc0
	s_and_b32 s35, s35, 62
	s_or_b32 s3, s35, s3
	s_bfe_u32 s2, s2, 0x10005
	s_or_b32 s35, s3, s2
	s_and_b64 s[2:3], s[44:45], exec
	s_cselect_b32 s2, s35, s31
	s_branch .LBB0_427
